# bias1 (pos@w1) restructured: 4 outputs per workgroup, K split over waves/lanes, coalesced 16B row pieces, LDS reduce; on workgroups 128..255
# speedup vs baseline: 1.0238x; 1.0017x over previous
; __device__ __forceinline__ float wave_sum(float v) { v += __shfl_xor(v, 1); v += __shfl_xor(v, 2); v += __shfl_xor(v, 4); v += __shfl_xor(v, 8); v += __shfl_xor(v, 16); v += __shfl_xor(v, 32); return v; }
; #define INP(k) ({ int k_ = (k); LAUNDER_S(k_); (const float*)(const GAS float*)P.in[k_]; })
; __global__ void __launch_bounds__(512, 2) hybrid_fwd(Params P) {
;     ...
;             if (gwave < 512) { const int kv = gwave >> 8, j = gwave & 255; const float* pp = INP(8) + (size_t)L * 2 * 2048 + kv * 2048; const float* ww = cw1 + (size_t)kv * 2048 * 256 + j; float a = 0.f;
; #pragma unroll 8
;                 for (int i = lane; i < 2048; i += 64) a = fmaf(pp[i], ww[(size_t)i * 256], a);
;                 a = wave_sum(a);
;                 if (lane == 0) ((float*)(ws + WS_SMALL))[kv * 256 + j] = a; }
;             if (L == 0 && bx == 2 && tid < 64) ((unsigned*)(ws + WS_CTL))[tid] = 0u;
.LBB0_391:
	s_addk_i32 s4, 0x400
	s_lshl_b32 s5, s27, 3
	s_cmp_ge_u32 s4, s5
	s_cselect_b32 s5, s5, 0
	s_sub_u32 s4, s4, s5
	s_cmpk_gt_i32 s4, 0x3ff
	s_cbranch_scc1 .LBB0_397
	s_load_dwordx2 s[18:19], s[0:1], 0x40
	s_lshr_b32 s5, s4, 3
	s_and_b32 s11, s4, 7
	s_lshr_b32 s16, s5, 6
	s_and_b32 s17, s5, 63
	s_lshl_b32 s20, s16, 21
	s_lshl_b32 s21, s11, 18
	s_add_u32 s20, s20, s21
	s_lshl_b32 s21, s17, 4
	s_add_u32 s20, s20, s21
	s_add_u32 s6, s6, s14
	s_addc_u32 s7, s7, s15
	s_add_u32 s6, s6, s20
	s_addc_u32 s7, s7, 0
	s_lshl_b32 s20, s10, 14
	s_lshl_b32 s21, s16, 13
	s_add_u32 s20, s20, s21
	s_lshl_b32 s21, s11, 10
	s_add_u32 s20, s20, s21
	s_waitcnt vmcnt(0) lgkmcnt(0)
	s_add_u32 s18, s18, s20
	s_addc_u32 s19, s19, 0
	v_lshrrev_b32_e32 v36, 2, v33
	v_and_b32_e32 v37, 3, v33
	v_lshlrev_b32_e32 v38, 14, v36
	v_lshl_add_u32 v38, v37, 2, v38
	v_lshlrev_b32_e32 v39, 6, v36
	v_add_u32_e32 v40, 0x1000, v38
	v_add_u32_e32 v41, 0x3000, v38
	global_load_dwordx4 v[0:3], v39, s[18:19]
	global_load_dwordx4 v[4:7], v39, s[18:19] offset:16
	global_load_dwordx4 v[8:11], v39, s[18:19] offset:32
	global_load_dwordx4 v[12:15], v39, s[18:19] offset:48
	global_load_dword v16, v40, s[6:7] offset:-4096
	global_load_dword v17, v40, s[6:7] offset:-3072
	global_load_dword v18, v40, s[6:7] offset:-2048
	global_load_dword v19, v40, s[6:7] offset:-1024
	global_load_dword v20, v40, s[6:7]
	global_load_dword v21, v40, s[6:7] offset:1024
	global_load_dword v22, v40, s[6:7] offset:2048
	global_load_dword v23, v40, s[6:7] offset:3072
	global_load_dword v24, v41, s[6:7] offset:-4096
	global_load_dword v25, v41, s[6:7] offset:-3072
	global_load_dword v26, v41, s[6:7] offset:-2048
	global_load_dword v27, v41, s[6:7] offset:-1024
	global_load_dword v28, v41, s[6:7]
	global_load_dword v29, v41, s[6:7] offset:1024
	global_load_dword v30, v41, s[6:7] offset:2048
	global_load_dword v31, v41, s[6:7] offset:3072
	v_mov_b32_e32 v34, 0
	v_mov_b32_e32 v35, 0
	s_waitcnt vmcnt(12)
	v_fmac_f32_e32 v34, v0, v16
	v_fmac_f32_e32 v35, v1, v17
	v_fmac_f32_e32 v34, v2, v18
	v_fmac_f32_e32 v35, v3, v19
	s_waitcnt vmcnt(8)
	v_fmac_f32_e32 v34, v4, v20
	v_fmac_f32_e32 v35, v5, v21
	v_fmac_f32_e32 v34, v6, v22
	v_fmac_f32_e32 v35, v7, v23
	s_waitcnt vmcnt(4)
	v_fmac_f32_e32 v34, v8, v24
	v_fmac_f32_e32 v35, v9, v25
	v_fmac_f32_e32 v34, v10, v26
	v_fmac_f32_e32 v35, v11, v27
	s_waitcnt vmcnt(0)
	v_fmac_f32_e32 v34, v12, v28
	v_fmac_f32_e32 v35, v13, v29
	v_fmac_f32_e32 v34, v14, v30
	v_fmac_f32_e32 v35, v15, v31
	v_add_f32_e32 v34, v34, v35
	v_xor_b32_e32 v36, 4, v33
	v_lshlrev_b32_e32 v36, 2, v36
	ds_bpermute_b32 v35, v36, v34
	s_waitcnt lgkmcnt(0)
	v_add_f32_e32 v34, v34, v35
	v_xor_b32_e32 v36, 8, v33
	v_lshlrev_b32_e32 v36, 2, v36
	ds_bpermute_b32 v35, v36, v34
	s_waitcnt lgkmcnt(0)
	v_add_f32_e32 v34, v34, v35
	v_xor_b32_e32 v36, 16, v33
	v_lshlrev_b32_e32 v36, 2, v36
	ds_bpermute_b32 v35, v36, v34
	s_waitcnt lgkmcnt(0)
	v_add_f32_e32 v34, v34, v35
	v_xor_b32_e32 v36, 32, v33
	v_lshlrev_b32_e32 v36, 2, v36
	ds_bpermute_b32 v35, v36, v34
	s_waitcnt lgkmcnt(0)
	v_add_f32_e32 v34, v34, v35
	v_lshlrev_b32_e32 v36, 2, v37
	s_lshl_b32 s20, s11, 4
	v_add_u32_e32 v38, s20, v36
	v_cmp_gt_u32_e32 vcc, 4, v33
	s_and_saveexec_b64 s[6:7], vcc
	ds_write_b32 v38, v34 offset:16384
	s_or_b64 exec, exec, s[6:7]
	s_waitcnt lgkmcnt(0)
	s_barrier
	s_cmp_lg_u32 s11, 0
	s_cbranch_scc1 .Lb1_done
	v_cmp_gt_u32_e32 vcc, 4, v33
	s_and_saveexec_b64 s[6:7], vcc
	ds_read_b32 v0, v36 offset:16384
	ds_read_b32 v1, v36 offset:16400
	ds_read_b32 v2, v36 offset:16416
	ds_read_b32 v3, v36 offset:16432
	ds_read_b32 v4, v36 offset:16448
	ds_read_b32 v5, v36 offset:16464
	ds_read_b32 v6, v36 offset:16480
	ds_read_b32 v7, v36 offset:16496
	s_waitcnt lgkmcnt(0)
	v_add_f32_e32 v0, v0, v1
	v_add_f32_e32 v2, v2, v3
	v_add_f32_e32 v4, v4, v5
	v_add_f32_e32 v6, v6, v7
	v_add_f32_e32 v0, v0, v2
	v_add_f32_e32 v4, v4, v6
	v_add_f32_e32 v0, v0, v4
	s_lshl_b32 s4, s5, 4
	s_add_u32 s4, s8, s4
	s_addc_u32 s5, s9, 0
	v_add_u32_e32 v1, 0x2400000, v36
	global_store_dword v1, v0, s[4:5]
	s_or_b64 exec, exec, s[6:7]
.Lb1_done:
.LBB0_397:
	s_cmp_eq_u32 s26, 2
	s_cselect_b64 s[4:5], -1, 0
	s_and_b64 s[6:7], s[12:13], s[4:5]
	v_cmp_gt_i32_e64 s[4:5], 64, v32
	v_cmp_lt_i32_e32 vcc, 63, v32
	s_and_b64 s[6:7], s[6:7], s[4:5]
	s_waitcnt vmcnt(1)
	v_ashrrev_i32_e32 v2, 31, v32
	s_and_saveexec_b64 s[4:5], s[6:7]
	s_cbranch_execz .LBB0_399
	v_mov_b32_e32 v33, v2
	s_waitcnt lgkmcnt(0)
	v_lshl_add_u64 v[0:1], v[32:33], 2, s[8:9]
	global_store_dword v[0:1], v81, off

;     __host__ __device__ bool next(int i, Unit& u) const {
;         const long L = (long)i * G + c; if (L >= nwg) return false;
;         int wgid = (int)L; { const int q = nwg / NXCD, r = nwg % NXCD, xcd = wgid % NXCD, off = wgid / NXCD; wgid = (xcd < r ? xcd * (q + 1) : r * (q + 1) + (xcd - r) * q) + off; }
;         const int nig = WGM * nN, gid = wgid / nig, fm = gid * WGM, gsz = (nM - fm) < WGM ? (nM - fm) : WGM;
;         u.pm = fm + ((wgid % nig) % gsz); u.pn = (wgid % nig) / gsz; return true;
; __global__ void __launch_bounds__(512, 2) hybrid_fwd(Params P) {
;     ...
;             pg8::Gemm g{L == 0 ? (const bf16_t*)(ws + WS_H) : (const bf16_t*)POUT, (const bf16_t*)(ws + WS_WIN), MTOK, NINP, DM, DM, DM}; pg8::StaticOrder S; S.init(MTOK, NINP, G, bx);
.LBB0_423:
	s_nop 0
	s_nop 0
	s_nop 0
	s_nop 0
	s_nop 0
	s_nop 0
	s_nop 0
	s_nop 0
	s_nop 0
	s_nop 0
	s_nop 0
	s_nop 0
	s_nop 0
	s_nop 0
	s_or_b64 exec, exec, s[4:5]
	s_mov_b32 s10, s20
	s_mov_b64 s[4:5], s[58:59]
	s_mov_b32 s52, s69
	s_mov_b32 s53, s2
	s_barrier
	v_mov_b32_e32 v8, v146
	s_cmpk_lt_i32 s53, 0xc00
	s_cselect_b64 s[6:7], -1, 0
	s_cmpk_gt_i32 s53, 0xbff
	v_readfirstlane_b32 s20, v8
	s_cbranch_scc1 .LBB0_425
	s_ashr_i32 s8, s53, 31
	s_lshr_b32 s8, s8, 29
	s_add_i32 s8, s53, s8
	s_ashr_i32 s9, s8, 3
	s_and_b32 s8, s8, -8
	s_sub_i32 s8, s53, s8
	s_cmp_lt_i32 s8, 0
	s_movk_i32 s11, 0x181
	s_cselect_b32 s11, s11, 0x180
	s_mul_i32 s8, s8, s11
	s_add_i32 s8, s8, s9
	s_mul_hi_i32 s9, s8, 0x2aaaaaab
	s_lshr_b32 s11, s9, 31
	s_ashr_i32 s9, s9, 5
	s_add_i32 s9, s9, s11
	s_lshl_b32 s11, s9, 3
	s_mulk_i32 s9, 0xc0
	s_sub_i32 s8, s8, s9
	s_bfe_u32 s9, s8, 0x3001c
	s_add_i32 s9, s8, s9
	s_sext_i32_i16 s12, s9
	s_and_b32 s9, s9, 0xfff8
	s_sub_i32 s8, s8, s9
	s_sext_i32_i16 s8, s8
	s_add_i32 s38, s11, s8
	s_ashr_i32 s36, s12, 3
